# v18 + V-piece DMA offsets in VGPRs (no per-piece SALU pointer math) + 4-chain row-max tree, placement kept
# baseline (speedup 1.0000x reference)
.LBB0_270:
	s_waitcnt lgkmcnt(0)
	v_max_f32_e32 v1, v1, v1
	v_max_f32_e32 v0, v0, v0
	v_max_f32_e32 v69, v0, v1
	v_sub_f32_e32 v32, v32, v69
	v_sub_f32_e32 v16, v16, v69
	v_sub_f32_e32 v33, v33, v69
	v_sub_f32_e32 v68, v46, v69
	v_sub_f32_e32 v46, v17, v69
	v_exp_f32_e32 v16, v16
	v_exp_f32_e32 v17, v32
	v_sub_f32_e32 v34, v34, v69
	v_sub_f32_e32 v70, v47, v69
	v_sub_f32_e32 v47, v18, v69
	v_sub_f32_e32 v71, v19, v69
	v_exp_f32_e32 v18, v46
	v_exp_f32_e32 v19, v33
	v_sub_f32_e32 v35, v35, v69
	v_sub_f32_e32 v72, v20, v69
	v_sub_f32_e32 v73, v21, v69
	v_exp_f32_e32 v20, v47
	v_exp_f32_e32 v21, v34
	v_sub_f32_e32 v36, v36, v69
	v_sub_f32_e32 v74, v22, v69
	v_sub_f32_e32 v75, v23, v69
	v_exp_f32_e32 v22, v71
	v_exp_f32_e32 v23, v35
	v_sub_f32_e32 v37, v37, v69
	v_sub_f32_e32 v76, v24, v69
	v_sub_f32_e32 v77, v25, v69
	v_sub_f32_e32 v78, v26, v69
	v_sub_f32_e32 v79, v27, v69
	v_pk_add_f32 v[24:25], v[16:17], 0 op_sel_hi:[1,0]
	v_exp_f32_e32 v26, v72
	v_exp_f32_e32 v27, v36
	v_sub_f32_e32 v38, v38, v69
	v_sub_f32_e32 v80, v28, v69
	v_sub_f32_e32 v81, v29, v69
	v_pk_add_f32 v[24:25], v[18:19], v[24:25]
	v_exp_f32_e32 v28, v73
	v_exp_f32_e32 v29, v37
	v_sub_f32_e32 v39, v39, v69
	v_sub_f32_e32 v82, v30, v69
	v_sub_f32_e32 v83, v31, v69
	v_pk_add_f32 v[24:25], v[20:21], v[24:25]
	v_exp_f32_e32 v30, v74
	v_exp_f32_e32 v31, v38
	v_sub_f32_e32 v40, v40, v69
	v_pk_add_f32 v[24:25], v[22:23], v[24:25]
	v_exp_f32_e32 v32, v75
	v_exp_f32_e32 v33, v39
	v_sub_f32_e32 v41, v41, v69
	v_exp_f32_e32 v34, v76
	v_exp_f32_e32 v35, v40
	v_pk_add_f32 v[24:25], v[26:27], v[24:25]
	v_sub_f32_e32 v42, v42, v69
	v_exp_f32_e32 v36, v77
	v_exp_f32_e32 v37, v41
	v_pk_add_f32 v[24:25], v[28:29], v[24:25]
	v_sub_f32_e32 v43, v43, v69
	v_exp_f32_e32 v38, v78
	v_exp_f32_e32 v39, v42
	v_pk_add_f32 v[24:25], v[30:31], v[24:25]
	v_sub_f32_e32 v44, v44, v69
	v_exp_f32_e32 v40, v79
	v_exp_f32_e32 v41, v43
	v_pk_add_f32 v[24:25], v[32:33], v[24:25]
	v_sub_f32_e32 v45, v45, v69
	v_exp_f32_e32 v42, v80
	v_exp_f32_e32 v43, v44
	v_pk_add_f32 v[24:25], v[34:35], v[24:25]
	v_exp_f32_e32 v44, v81
	v_exp_f32_e32 v45, v45
	v_pk_add_f32 v[24:25], v[36:37], v[24:25]
	v_exp_f32_e32 v46, v82
	v_exp_f32_e32 v47, v68
	v_pk_add_f32 v[24:25], v[38:39], v[24:25]
	v_exp_f32_e32 v82, v83
	v_exp_f32_e32 v83, v70
	v_pk_add_f32 v[24:25], v[40:41], v[24:25]
	s_add_i32 s64, s64, 1
	v_exp_f32_e64 v0, -v69
	v_pk_add_f32 v[24:25], v[42:43], v[24:25]
	s_cmp_lt_u32 s64, s37
	v_pk_add_f32 v[24:25], v[44:45], v[24:25]
	s_cselect_b32 s12, s96, 0
	v_pk_add_f32 v[24:25], v[46:47], v[24:25]
	s_add_i32 s27, s12, s27
	v_pk_add_f32 v[24:25], v[82:83], v[24:25]
	s_ashr_i32 s12, s27, 6
	s_bfe_u32 s54, s27, 0x20004
	v_mul_f32_e32 v0, 0, v0
	v_pk_add_f32 v[24:25], v[24:25], v[24:25] op_sel:[0,1] op_sel_hi:[1,0]
	s_lshl_b32 s36, s12, 4
	s_lshl_b32 s53, s54, 1
	v_mov_b32_e32 v68, v0
	v_mov_b32_e32 v25, v189
	s_or_b32 s53, s53, s36
	s_lshl_b32 s36, s63, 7
	s_and_b32 s55, s58, 0x780
	v_pk_add_f32 v[206:207], v[68:69], v[24:25]
	v_cvt_pk_bf16_f32 v68, v16, v18
	s_and_b32 s36, s36, 0x1800
	v_add_lshl_u32 v16, v158, s55, 2
	v_sub_u32_e32 v16, s36, v16
	v_cvt_pk_bf16_f32 v69, v20, v22
	v_cvt_pk_bf16_f32 v70, v26, v28
	v_cvt_pk_bf16_f32 v71, v30, v32
	v_cvt_pk_bf16_f32 v76, v17, v19
	v_cvt_pk_bf16_f32 v77, v21, v23
	v_cvt_pk_bf16_f32 v78, v27, v29
	v_cvt_pk_bf16_f32 v79, v31, v33
	v_add_u32_e32 v167, v215, v16
	ds_read_b128 v[16:19], v64 offset:20480
	ds_read_b128 v[20:23], v65 offset:20480
	ds_read_b128 v[24:27], v66 offset:20480
	ds_read_b128 v[28:31], v67 offset:20480
	s_lshl_b32 s54, s54, 7
	s_lshl_b32 s12, s12, 9
	v_mov_b32_e32 v1, v0
	v_mov_b32_e32 v2, v0
	v_mov_b32_e32 v3, v0
	v_mov_b32_e32 v4, v0
	v_mov_b32_e32 v5, v0
	v_mov_b32_e32 v6, v0
	v_mov_b32_e32 v7, v0
	v_mov_b32_e32 v8, v0
	v_mov_b32_e32 v9, v0
	v_mov_b32_e32 v10, v0
	v_mov_b32_e32 v11, v0
	v_mov_b32_e32 v12, v0
	v_mov_b32_e32 v13, v0
	v_mov_b32_e32 v14, v0
	v_mov_b32_e32 v15, v0
	s_mov_b32 s23, 0
	s_sub_i32 s36, s62, s55
	s_or_b32 s12, s54, s12
	v_cvt_pk_bf16_f32 v72, v34, v36
	v_cvt_pk_bf16_f32 v73, v38, v40
	v_cvt_pk_bf16_f32 v74, v42, v44
	v_cvt_pk_bf16_f32 v75, v46, v82
	v_cvt_pk_bf16_f32 v80, v35, v37
	v_cvt_pk_bf16_f32 v81, v39, v41
	v_cvt_pk_bf16_f32 v82, v43, v45
	v_cvt_pk_bf16_f32 v83, v47, v83
	v_mfma_f32_32x32x16_bf16 v[32:47], v[56:59], v[68:71], v[0:15]
	v_mfma_f32_32x32x16_bf16 v[32:47], v[48:51], v[72:75], v[32:47]
	v_mfma_f32_32x32x16_bf16 v[32:47], v[60:63], v[76:79], v[32:47]
	v_mfma_f32_32x32x16_bf16 v[32:47], v[52:55], v[80:83], v[32:47]
	s_add_i32 s54, s33, 0x8000
	s_and_b32 s54, s54, 0x18000
	v_add_u32_e32 v48, s54, v149
	v_add_u32_e32 v49, v48, v157
	ds_read_b128 v[132:135], v49
	ds_read_b128 v[116:119], v49 offset:4096
	v_add_u32_e32 v49, v48, v193
	ds_read_b128 v[136:139], v49
	ds_read_b128 v[120:123], v49 offset:4096
	v_add_u32_e32 v49, v48, v208
	v_add_u32_e32 v48, v48, v209
	ds_read_b128 v[140:143], v49
	ds_read_b128 v[124:127], v49 offset:4096
	ds_read_b128 v[128:131], v48
	ds_read_b128 v[112:115], v48 offset:4096
	ds_read_b128 v[84:87], v64 offset:24576
	ds_read_b128 v[88:91], v65 offset:24576
	ds_read_b128 v[92:95], v66 offset:24576
	ds_read_b128 v[216:219], v67 offset:24576
	s_waitcnt lgkmcnt(0)
	v_mfma_f32_32x32x16_bf16 v[48:63], v[16:19], v[68:71], v[0:15]
	v_mfma_f32_32x32x16_bf16 v[48:63], v[20:23], v[72:75], v[48:63]
	v_mfma_f32_32x32x16_bf16 v[48:63], v[24:27], v[76:79], v[48:63]
	v_mfma_f32_32x32x16_bf16 v[48:63], v[28:31], v[80:83], v[48:63]
	ds_read_b128 v[220:223], v64 offset:28672
	ds_read_b128 v[234:237], v65 offset:28672
	ds_read_b128 v[238:241], v66 offset:28672
	ds_read_b128 v[64:67], v67 offset:28672
	v_mfma_f32_32x32x16_bf16 v[16:31], v[84:87], v[68:71], v[0:15]
	v_mfma_f32_32x32x16_bf16 v[16:31], v[88:91], v[72:75], v[16:31]
	v_mfma_f32_32x32x16_bf16 v[16:31], v[92:95], v[76:79], v[16:31]
	v_mfma_f32_32x32x16_bf16 v[16:31], v[216:219], v[80:83], v[16:31]
	s_waitcnt lgkmcnt(0)
	v_mfma_f32_32x32x16_bf16 v[0:15], v[220:223], v[68:71], v[0:15]
	s_waitcnt lgkmcnt(0)
	s_barrier
	s_add_i32 s65, s33, 0x10000
	s_mov_b32 s33, 0
	v_mfma_f32_32x32x16_bf16 v[0:15], v[234:237], v[72:75], v[0:15]
	v_mfma_f32_32x32x16_bf16 v[0:15], v[238:241], v[76:79], v[0:15]
	v_mfma_f32_32x32x16_bf16 v[0:15], v[64:67], v[80:83], v[0:15]
	s_setprio 0
	s_nop 0
	s_nop 0
	s_nop 0
	s_nop 0
	s_nop 0
	s_nop 0
	s_nop 0
	s_nop 0
	s_nop 0
	v_lshlrev_b32_e32 v198, 1, v150
	v_add_u32_e32 v199, 0x40000, v198
	v_add_u32_e32 v204, 0x20000, v198
	v_add_u32_e32 v205, 0x60000, v198
	s_and_b64 vcc, exec, s[42:43]
	s_cbranch_vccnz .LqT_top

.LqL_rest:
	v_add_u32_e32 v116, s54, v214
	v_add_u32_e32 v216, v116, v157
	v_add_u32_e32 v218, v116, v208
	v_add_u32_e32 v217, v116, v193
	v_add_u32_e32 v219, v116, v209
	v_mfma_f32_32x32x16_bf16 v[64:79], v[136:139], v[104:107], v[64:79]
	v_mfma_f32_32x32x16_bf16 v[80:95], v[120:123], v[104:107], v[80:95]
	v_mfma_f32_32x32x16_bf16 v[64:79], v[140:143], v[100:103], v[64:79]
	v_mfma_f32_32x32x16_bf16 v[80:95], v[124:127], v[100:103], v[80:95]
	v_mfma_f32_32x32x16_bf16 v[80:95], v[112:115], v[96:99], v[80:95]
	ds_read_b128 v[242:245], v216 offset:16384
	ds_read_b128 v[246:249], v216 offset:20480
	ds_read_b128 v[250:253], v216 offset:24576
	ds_read_b128 v[200:203], v216 offset:28672
	ds_read_b128 v[220:223], v217 offset:16384
	ds_read_b128 v[224:227], v217 offset:20480
	ds_read_b128 v[234:237], v217 offset:24576
	ds_read_b128 v[238:241], v217 offset:28672
	v_mfma_f32_32x32x16_bf16 v[64:79], v[128:131], v[96:99], v[64:79]
	s_nop 5
	v_max3_f32 v128, v80, v81, v82
	v_max3_f32 v129, v83, v84, v85
	v_max3_f32 v130, v86, v87, v88
	v_max3_f32 v131, v89, v90, v91
	v_max3_f32 v128, v128, v92, v93
	v_max3_f32 v129, v129, v94, v95
	v_max3_f32 v130, v130, v64, v65
	v_max3_f32 v131, v131, v66, v67
	v_max3_f32 v128, v128, v68, v69
	v_max3_f32 v129, v129, v70, v71
	v_max3_f32 v130, v130, v72, v73
	v_max3_f32 v131, v131, v74, v75
	v_max3_f32 v128, v128, v76, v77
	v_max3_f32 v129, v129, v78, v79
	v_max3_f32 v128, v128, v129, v130
	v_max_f32_e32 v128, v128, v131
	v_cmp_lt_f32_e32 vcc, s88, v128
	s_cbranch_vccnz .LqL_rescale

.LqL_ldsb:
	s_add_i32 s33, s65, 0x10000
	s_and_b32 s33, s33, 0x18000
	s_add_i32 s33, s57, s33
	v_mfma_f32_32x32x16_bf16 v[32:47], v[242:245], v[64:67], v[32:47]
	s_mov_b32 m0, s33
	v_exp_f32_e32 v72, v72
	v_exp_f32_e32 v73, v73
	v_exp_f32_e32 v74, v74
	v_exp_f32_e32 v75, v75
	v_add_f32_e32 v184, v72, v73
	s_and_b32 s100, s65, 0x18000
	v_add_u32_e32 v194, s100, v149
	v_add_u32_e32 v195, v194, v157
	v_add_u32_e32 v196, v194, v193
	ds_read_b128 v[242:245], v218 offset:16384
	global_load_lds_dwordx4 v188, s[70:71]
	v_mfma_f32_32x32x16_bf16 v[48:63], v[246:249], v[64:67], v[48:63]
	v_exp_f32_e32 v76, v76
	v_exp_f32_e32 v77, v77
	v_cvt_pk_bf16_f32 v68, v72, v73
	v_add_f32_e32 v185, v74, v75
	v_cvt_pk_bf16_f32 v69, v74, v75
	v_add_u32_e32 v197, v194, v208
	v_add_u32_e32 v194, v194, v209
	ds_read_b128 v[132:135], v195
	ds_read_b128 v[116:119], v195 offset:4096
	ds_read_b128 v[246:249], v218 offset:20480
	v_mfma_f32_32x32x16_bf16 v[16:31], v[250:253], v[64:67], v[16:31]
	s_add_u32 s100, s70, 0x40000
	s_addc_u32 s101, s71, 0
	s_add_i32 m0, s33, 0x2000
	v_exp_f32_e32 v78, v78
	v_exp_f32_e32 v79, v79
	v_add_f32_e32 v186, v76, v77
	v_cvt_pk_bf16_f32 v70, v76, v77
	v_add_f32_e32 v184, v184, v185
	ds_read_b128 v[136:139], v196
	ds_read_b128 v[120:123], v196 offset:4096
	ds_read_b128 v[140:143], v197
	ds_read_b128 v[124:127], v197 offset:4096
	ds_read_b128 v[250:253], v218 offset:24576
	global_load_lds_dwordx4 v188, s[100:101]
	v_mfma_f32_32x32x16_bf16 v[0:15], v[200:203], v[64:67], v[0:15]
	v_add_f32_e32 v187, v78, v79
	v_cvt_pk_bf16_f32 v71, v78, v79
	v_add_f32_e32 v186, v186, v187
	v_add_f32_e32 v184, v184, v186
	v_add_f32_e32 v206, v206, v184
	ds_read_b128 v[128:131], v194
	ds_read_b128 v[112:115], v194 offset:4096
	ds_read_b128 v[200:203], v218 offset:28672
	v_mfma_f32_32x32x16_bf16 v[32:47], v[220:223], v[68:71], v[32:47]
	s_add_i32 m0, s33, 0x4000
	v_exp_f32_e32 v80, v80
	v_exp_f32_e32 v81, v81
	v_exp_f32_e32 v82, v82
	v_exp_f32_e32 v83, v83
	v_add_f32_e32 v184, v80, v81
	ds_read_b128 v[220:223], v219 offset:16384
	global_load_lds_dwordx4 v198, s[66:67]
	v_mfma_f32_32x32x16_bf16 v[48:63], v[224:227], v[68:71], v[48:63]
	v_exp_f32_e32 v84, v84
	v_exp_f32_e32 v85, v85
	v_cvt_pk_bf16_f32 v72, v80, v81
	v_add_f32_e32 v185, v82, v83
	v_cvt_pk_bf16_f32 v73, v82, v83
	ds_read_b128 v[224:227], v219 offset:20480
	v_mfma_f32_32x32x16_bf16 v[16:31], v[234:237], v[68:71], v[16:31]
	s_add_i32 m0, s33, 0x6000
	v_exp_f32_e32 v86, v86
	v_exp_f32_e32 v87, v87
	v_add_f32_e32 v186, v84, v85
	v_cvt_pk_bf16_f32 v74, v84, v85
	v_add_f32_e32 v184, v184, v185
	ds_read_b128 v[234:237], v219 offset:24576
	global_load_lds_dwordx4 v199, s[66:67]
	v_mfma_f32_32x32x16_bf16 v[0:15], v[238:241], v[68:71], v[0:15]
	v_add_f32_e32 v187, v86, v87
	v_cvt_pk_bf16_f32 v75, v86, v87
	v_add_f32_e32 v186, v186, v187
	v_add_f32_e32 v184, v184, v186
	v_add_f32_e32 v206, v206, v184
	ds_read_b128 v[238:241], v219 offset:28672
	s_waitcnt lgkmcnt(4)
	v_mfma_f32_32x32x16_bf16 v[32:47], v[242:245], v[72:75], v[32:47]
	s_add_u32 s100, s70, 0x1000
	s_addc_u32 s101, s71, 0
	s_add_i32 m0, s33, 0x1000
	v_exp_f32_e32 v88, v88
	v_exp_f32_e32 v89, v89
	v_exp_f32_e32 v90, v90
	v_exp_f32_e32 v91, v91
	v_add_f32_e32 v184, v88, v89
	global_load_lds_dwordx4 v188, s[100:101]
	v_mfma_f32_32x32x16_bf16 v[48:63], v[246:249], v[72:75], v[48:63]
	v_exp_f32_e32 v92, v92
	v_exp_f32_e32 v93, v93
	v_cvt_pk_bf16_f32 v76, v88, v89
	v_add_f32_e32 v185, v90, v91
	v_cvt_pk_bf16_f32 v77, v90, v91
	v_mfma_f32_32x32x16_bf16 v[16:31], v[250:253], v[72:75], v[16:31]
	s_add_u32 s100, s70, 0x41000
	s_addc_u32 s101, s71, 0
	s_add_i32 m0, s33, 0x3000
	v_exp_f32_e32 v94, v94
	v_exp_f32_e32 v95, v95
	v_add_f32_e32 v186, v92, v93
	v_cvt_pk_bf16_f32 v78, v92, v93
	v_add_f32_e32 v184, v184, v185
	global_load_lds_dwordx4 v188, s[100:101]
	v_mfma_f32_32x32x16_bf16 v[0:15], v[200:203], v[72:75], v[0:15]
	v_add_f32_e32 v187, v94, v95
	v_cvt_pk_bf16_f32 v79, v94, v95
	v_add_f32_e32 v186, v186, v187
	v_add_f32_e32 v184, v184, v186
	v_add_f32_e32 v206, v206, v184
	s_waitcnt lgkmcnt(0)
	v_mfma_f32_32x32x16_bf16 v[32:47], v[220:223], v[76:79], v[32:47]
	s_add_i32 m0, s33, 0x5000
	s_nop 0
	global_load_lds_dwordx4 v204, s[66:67]
	v_mfma_f32_32x32x16_bf16 v[48:63], v[224:227], v[76:79], v[48:63]
	s_add_i32 m0, s33, 0x7000
	s_nop 0
	global_load_lds_dwordx4 v205, s[66:67]
	s_waitcnt lgkmcnt(0)
	s_add_i32 s65, s65, 0x8000
	s_addk_i32 s23, 0x100
	s_add_i32 s36, s36, 64
	s_mov_b32 s33, s54
	s_cmpk_eq_i32 s23, 0x1e00
	v_mfma_f32_32x32x16_bf16 v[16:31], v[234:237], v[76:79], v[16:31]
	v_mfma_f32_32x32x16_bf16 v[0:15], v[238:241], v[76:79], v[0:15]
	s_setprio 0
	s_cbranch_scc0 .LqL_top
	s_branch .LBB0_284

.LqL_full:
	s_cmp_lt_u32 s54, 29
	s_cselect_b32 s67, s13, s53
	s_cselect_b32 s55, 3, 0xffffffe3
	s_cselect_b32 s66, s22, s12
	s_or_b32 s70, s67, 8
	s_add_i32 s33, s55, s33
	s_ashr_i32 s71, s70, 31
	s_add_i32 s68, s33, 1
	s_lshl_b64 s[70:71], s[70:71], 18
	s_add_u32 s33, s8, s70
	s_addc_u32 s55, s9, s71
	s_ashr_i32 s69, s68, 31
	s_lshl_b64 s[70:71], s[68:69], 13
	s_add_u32 s70, s33, s70
	s_addc_u32 s71, s55, s71
	s_ashr_i32 s67, s66, 31
	s_lshl_b64 s[66:67], s[66:67], 12
	s_add_u32 s33, s10, s66
	s_addc_u32 s55, s11, s67
	s_lshl_b32 s66, s68, 6
	s_ashr_i32 s67, s66, 31
	s_lshl_b64 s[66:67], s[66:67], 1
	s_add_u32 s66, s33, s66
	s_addc_u32 s67, s55, s67
	s_branch .LqL_ldsb
	s_nop 0
	s_nop 0
	s_nop 0
	s_nop 0
	s_nop 0
	s_nop 0
	s_nop 0
	s_nop 0
	s_nop 0
	s_nop 0
	s_nop 0
	s_nop 0

.LqT_rescale:
	s_mov_b32 s98, 0
	ds_bpermute_b32 v129, v210, v128
	s_waitcnt lgkmcnt(0)
	v_max_f32_e32 v129, v129, v129
	v_max_f32_e32 v128, v128, v129
	v_cmp_lt_f32_e32 vcc, s88, v128
	s_nop 0
	s_nop 0
	v_cndmask_b32_e32 v128, 0, v128, vcc
	v_exp_f32_e64 v130, -v128
	v_pk_add_f32 v[64:65], v[64:65], v[128:129] op_sel_hi:[1,0] neg_lo:[0,1] neg_hi:[0,1]
	v_pk_add_f32 v[80:81], v[80:81], v[128:129] op_sel_hi:[1,0] neg_lo:[0,1] neg_hi:[0,1]
	v_pk_add_f32 v[66:67], v[66:67], v[128:129] op_sel_hi:[1,0] neg_lo:[0,1] neg_hi:[0,1]
	v_pk_mul_f32 v[46:47], v[46:47], v[130:131] op_sel_hi:[1,0]
	v_pk_mul_f32 v[44:45], v[44:45], v[130:131] op_sel_hi:[1,0]
	v_pk_mul_f32 v[42:43], v[42:43], v[130:131] op_sel_hi:[1,0]
	v_pk_mul_f32 v[40:41], v[40:41], v[130:131] op_sel_hi:[1,0]
	v_pk_mul_f32 v[38:39], v[38:39], v[130:131] op_sel_hi:[1,0]
	v_pk_mul_f32 v[36:37], v[36:37], v[130:131] op_sel_hi:[1,0]
	v_pk_mul_f32 v[34:35], v[34:35], v[130:131] op_sel_hi:[1,0]
	v_pk_mul_f32 v[32:33], v[32:33], v[130:131] op_sel_hi:[1,0]
	v_pk_mul_f32 v[62:63], v[62:63], v[130:131] op_sel_hi:[1,0]
	v_pk_mul_f32 v[60:61], v[60:61], v[130:131] op_sel_hi:[1,0]
	v_pk_mul_f32 v[58:59], v[58:59], v[130:131] op_sel_hi:[1,0]
	v_pk_mul_f32 v[56:57], v[56:57], v[130:131] op_sel_hi:[1,0]
	v_pk_mul_f32 v[54:55], v[54:55], v[130:131] op_sel_hi:[1,0]
	v_pk_mul_f32 v[52:53], v[52:53], v[130:131] op_sel_hi:[1,0]
	v_pk_mul_f32 v[50:51], v[50:51], v[130:131] op_sel_hi:[1,0]
	v_pk_mul_f32 v[48:49], v[48:49], v[130:131] op_sel_hi:[1,0]
	v_pk_mul_f32 v[30:31], v[30:31], v[130:131] op_sel_hi:[1,0]
	v_pk_mul_f32 v[28:29], v[28:29], v[130:131] op_sel_hi:[1,0]
	v_pk_mul_f32 v[26:27], v[26:27], v[130:131] op_sel_hi:[1,0]
	v_pk_mul_f32 v[24:25], v[24:25], v[130:131] op_sel_hi:[1,0]
	v_pk_mul_f32 v[22:23], v[22:23], v[130:131] op_sel_hi:[1,0]
	v_pk_mul_f32 v[20:21], v[20:21], v[130:131] op_sel_hi:[1,0]
	v_pk_mul_f32 v[18:19], v[18:19], v[130:131] op_sel_hi:[1,0]
	v_pk_mul_f32 v[16:17], v[16:17], v[130:131] op_sel_hi:[1,0]
	v_pk_mul_f32 v[14:15], v[14:15], v[130:131] op_sel_hi:[1,0]
	v_pk_mul_f32 v[12:13], v[12:13], v[130:131] op_sel_hi:[1,0]
	v_pk_mul_f32 v[10:11], v[10:11], v[130:131] op_sel_hi:[1,0]
	v_pk_mul_f32 v[8:9], v[8:9], v[130:131] op_sel_hi:[1,0]
	v_pk_mul_f32 v[6:7], v[6:7], v[130:131] op_sel_hi:[1,0]
	v_pk_mul_f32 v[4:5], v[4:5], v[130:131] op_sel_hi:[1,0]
	v_pk_mul_f32 v[2:3], v[2:3], v[130:131] op_sel_hi:[1,0]
	v_pk_mul_f32 v[0:1], v[0:1], v[130:131] op_sel_hi:[1,0]
	v_mov_b32_e32 v131, v128
	v_pk_add_f32 v[82:83], v[82:83], v[128:129] op_sel_hi:[1,0] neg_lo:[0,1] neg_hi:[0,1]
	v_pk_add_f32 v[68:69], v[68:69], v[128:129] op_sel_hi:[1,0] neg_lo:[0,1] neg_hi:[0,1]
	v_pk_add_f32 v[84:85], v[84:85], v[128:129] op_sel_hi:[1,0] neg_lo:[0,1] neg_hi:[0,1]
	v_pk_add_f32 v[70:71], v[70:71], v[128:129] op_sel_hi:[1,0] neg_lo:[0,1] neg_hi:[0,1]
	v_pk_add_f32 v[86:87], v[86:87], v[128:129] op_sel_hi:[1,0] neg_lo:[0,1] neg_hi:[0,1]
	v_pk_add_f32 v[72:73], v[72:73], v[128:129] op_sel_hi:[1,0] neg_lo:[0,1] neg_hi:[0,1]
	v_pk_add_f32 v[88:89], v[88:89], v[128:129] op_sel_hi:[1,0] neg_lo:[0,1] neg_hi:[0,1]
	v_pk_add_f32 v[74:75], v[74:75], v[128:129] op_sel_hi:[1,0] neg_lo:[0,1] neg_hi:[0,1]
	v_pk_add_f32 v[90:91], v[90:91], v[128:129] op_sel_hi:[1,0] neg_lo:[0,1] neg_hi:[0,1]
	v_pk_add_f32 v[76:77], v[76:77], v[128:129] op_sel_hi:[1,0] neg_lo:[0,1] neg_hi:[0,1]
	v_pk_add_f32 v[92:93], v[92:93], v[128:129] op_sel_hi:[1,0] neg_lo:[0,1] neg_hi:[0,1]
	v_pk_add_f32 v[78:79], v[78:79], v[128:129] op_sel_hi:[1,0] neg_lo:[0,1] neg_hi:[0,1]
	v_pk_add_f32 v[94:95], v[94:95], v[128:129] op_sel_hi:[1,0] neg_lo:[0,1] neg_hi:[0,1]
	v_pk_add_f32 v[128:129], v[206:207], v[130:131]
	v_pk_mul_f32 v[206:207], v[206:207], v[130:131]
	s_nop 0
	v_mov_b32_e32 v207, v129
	s_branch .LqT_g0
	s_nop 0
	s_nop 0
	s_nop 0
	s_nop 0
